# remove redundant buffer_inv sc1 in the 3 fused-LN epilogues (slot loads are sc1, L1 acquire not needed)
# baseline (speedup 1.0000x reference)
.LBB0_274:
	s_waitcnt vmcnt(0)
	s_and_b64 exec, exec, s[12:13]
	s_cbranch_execz .LBB0_276
	v_readlane_b32 s2, v254, 23
	v_cndmask_b32_e64 v112, 0, 1, s[56:57]
	s_nop 0
	v_mov_b32_e32 v113, s2
	ds_write_b32 v113, v112

.LBB0_682:
	s_waitcnt vmcnt(0)
	s_and_b64 exec, exec, s[12:13]
	s_cbranch_execz .LBB0_684
	v_readlane_b32 s18, v254, 23
	v_cndmask_b32_e64 v112, 0, 1, s[28:29]
	s_nop 0
	v_mov_b32_e32 v113, s18
	ds_write_b32 v113, v112

.LBB0_852:
	s_waitcnt vmcnt(0)
	s_and_b64 exec, exec, s[12:13]
	s_cbranch_execz .LBB0_854
	v_readlane_b32 s6, v254, 23
	v_cndmask_b32_e64 v76, 0, 1, s[82:83]
	s_nop 0
	v_mov_b32_e32 v77, s6
	ds_write_b32 v77, v76
